# v085: v084 + the same nt hint on the read-once f32 weight loads of the deferred weight conversion (first B layer FFN-up idle round)
# speedup vs baseline: 1.0155x; 1.0011x over previous
.LBB0_2980:
	v_mov_b32_e32 v69, v2
	s_cmp_lt_i32 s21, s42
	v_ashrrev_i32_e32 v133, 4, v3
	v_cmp_lt_i32_e32 vcc, -1, v68
	s_cselect_b64 s[16:17], -1, 0
	s_cmp_ge_i32 s21, s42
	v_lshl_add_u64 v[134:135], v[68:69], 2, s[80:81]
	s_cbranch_scc1 .LBB0_2990
	v_add_u32_e32 v84, s0, v133
	v_mov_b32_e32 v72, 0
	v_mov_b32_e32 v68, 0
	v_mov_b32_e32 v69, 0
	v_mov_b32_e32 v70, 0
	v_mov_b32_e32 v71, 0
	s_and_saveexec_b64 s[18:19], vcc
	s_cbranch_execz .LBB0_2983
	v_ashrrev_i32_e32 v68, 31, v84
	v_mul_lo_u32 v70, s87, v84
	v_mul_lo_u32 v71, s86, v68
	v_mad_u64_u32 v[68:69], s[72:73], s86, v84, 0
	v_add3_u32 v69, v69, v71, v70
	v_lshl_add_u64 v[68:69], v[68:69], 2, v[134:135]
	global_load_dwordx4 v[68:71], v[68:69], off nt
.LBB0_2983:
	s_or_b64 exec, exec, s[18:19]
	v_mov_b32_e32 v73, 0
	v_mov_b32_e32 v74, 0
	v_mov_b32_e32 v75, 0
	s_and_saveexec_b64 s[18:19], vcc
	s_cbranch_execz .LBB0_2985
	v_add_u32_e32 v72, 32, v84
	v_ashrrev_i32_e32 v73, 31, v72
	v_mul_lo_u32 v74, s86, v73
	v_mul_lo_u32 v75, s87, v72
	v_mad_u64_u32 v[72:73], s[72:73], s86, v72, 0
	v_add3_u32 v73, v73, v74, v75
	v_lshl_add_u64 v[72:73], v[72:73], 2, v[134:135]
	global_load_dwordx4 v[72:75], v[72:73], off nt
.LBB0_2985:
	s_or_b64 exec, exec, s[18:19]
	v_mov_b32_e32 v79, 0
	v_mov_b32_e32 v80, 0
	v_mov_b32_e32 v81, 0
	v_mov_b32_e32 v82, 0
	v_mov_b32_e32 v83, 0
	s_and_saveexec_b64 s[18:19], vcc
	s_cbranch_execz .LBB0_2987
	v_add_u32_e32 v76, 64, v84
	v_ashrrev_i32_e32 v77, 31, v76
	v_mul_lo_u32 v78, s86, v77
	v_mul_lo_u32 v80, s87, v76
	v_mad_u64_u32 v[76:77], s[72:73], s86, v76, 0
	v_add3_u32 v77, v77, v78, v80
	v_lshl_add_u64 v[76:77], v[76:77], 2, v[134:135]
	global_load_dwordx4 v[80:83], v[76:77], off nt
.LBB0_2987:
	s_or_b64 exec, exec, s[18:19]
	v_mov_b32_e32 v78, 0
	v_mov_b32_e32 v77, 0
	v_mov_b32_e32 v76, 0
	s_and_saveexec_b64 s[18:19], vcc
	s_cbranch_execz .LBB0_2989
	v_add_u32_e32 v76, 0x60, v84
	v_ashrrev_i32_e32 v77, 31, v76
	v_mul_lo_u32 v78, s86, v77
	v_mul_lo_u32 v79, s87, v76
	v_mad_u64_u32 v[76:77], s[72:73], s86, v76, 0
	v_add3_u32 v77, v77, v78, v79
	v_lshl_add_u64 v[76:77], v[76:77], 2, v[134:135]
	global_load_dwordx4 v[76:79], v[76:77], off nt

.LBB0_2990:
	s_cmp_lt_i32 s20, s42
	s_cselect_b64 s[18:19], -1, 0
	s_cmp_ge_i32 s20, s42
	s_cbranch_scc1 .LBB0_3000
	v_add_u32_e32 v100, s52, v133
	v_mov_b32_e32 v88, 0
	v_mov_b32_e32 v84, 0
	v_mov_b32_e32 v85, 0
	v_mov_b32_e32 v86, 0
	v_mov_b32_e32 v87, 0
	s_and_saveexec_b64 s[20:21], vcc
	s_cbranch_execz .LBB0_2993
	v_ashrrev_i32_e32 v84, 31, v100
	v_mul_lo_u32 v86, s87, v100
	v_mul_lo_u32 v87, s86, v84
	v_mad_u64_u32 v[84:85], s[72:73], s86, v100, 0
	v_add3_u32 v85, v85, v87, v86
	v_lshl_add_u64 v[84:85], v[84:85], 2, v[134:135]
	global_load_dwordx4 v[84:87], v[84:85], off nt
.LBB0_2993:
	s_or_b64 exec, exec, s[20:21]
	v_mov_b32_e32 v89, 0
	v_mov_b32_e32 v90, 0
	v_mov_b32_e32 v91, 0
	s_and_saveexec_b64 s[20:21], vcc
	s_cbranch_execz .LBB0_2995
	v_add_u32_e32 v88, 32, v100
	v_ashrrev_i32_e32 v89, 31, v88
	v_mul_lo_u32 v90, s86, v89
	v_mul_lo_u32 v91, s87, v88
	v_mad_u64_u32 v[88:89], s[72:73], s86, v88, 0
	v_add3_u32 v89, v89, v90, v91
	v_lshl_add_u64 v[88:89], v[88:89], 2, v[134:135]
	global_load_dwordx4 v[88:91], v[88:89], off nt
.LBB0_2995:
	s_or_b64 exec, exec, s[20:21]
	v_mov_b32_e32 v95, 0
	v_mov_b32_e32 v96, 0
	v_mov_b32_e32 v97, 0
	v_mov_b32_e32 v98, 0
	v_mov_b32_e32 v99, 0
	s_and_saveexec_b64 s[20:21], vcc
	s_cbranch_execz .LBB0_2997
	v_add_u32_e32 v92, 64, v100
	v_ashrrev_i32_e32 v93, 31, v92
	v_mul_lo_u32 v94, s86, v93
	v_mul_lo_u32 v96, s87, v92
	v_mad_u64_u32 v[92:93], s[72:73], s86, v92, 0
	v_add3_u32 v93, v93, v94, v96
	v_lshl_add_u64 v[92:93], v[92:93], 2, v[134:135]
	global_load_dwordx4 v[96:99], v[92:93], off nt
.LBB0_2997:
	s_or_b64 exec, exec, s[20:21]
	v_mov_b32_e32 v94, 0
	v_mov_b32_e32 v93, 0
	v_mov_b32_e32 v92, 0
	s_and_saveexec_b64 s[20:21], vcc
	s_cbranch_execz .LBB0_2999
	v_add_u32_e32 v92, 0x60, v100
	v_ashrrev_i32_e32 v93, 31, v92
	v_mul_lo_u32 v94, s86, v93
	v_mul_lo_u32 v95, s87, v92
	v_mad_u64_u32 v[92:93], s[72:73], s86, v92, 0
	v_add3_u32 v93, v93, v94, v95
	v_lshl_add_u64 v[92:93], v[92:93], 2, v[134:135]
	global_load_dwordx4 v[92:95], v[92:93], off nt

.LBB0_3000:
	s_cmp_lt_i32 s22, s42
	s_cselect_b64 s[72:73], -1, 0
	s_cmp_ge_i32 s22, s42
	s_cbranch_scc1 .LBB0_3010
	v_add_u32_e32 v116, s14, v133
	v_mov_b32_e32 v104, 0
	v_mov_b32_e32 v100, 0
	v_mov_b32_e32 v101, 0
	v_mov_b32_e32 v102, 0
	v_mov_b32_e32 v103, 0
	s_and_saveexec_b64 s[20:21], vcc
	s_cbranch_execz .LBB0_3003
	v_ashrrev_i32_e32 v100, 31, v116
	v_mul_lo_u32 v102, s87, v116
	v_mul_lo_u32 v103, s86, v100
	v_mad_u64_u32 v[100:101], s[22:23], s86, v116, 0
	v_add3_u32 v101, v101, v103, v102
	v_lshl_add_u64 v[100:101], v[100:101], 2, v[134:135]
	global_load_dwordx4 v[100:103], v[100:101], off nt
.LBB0_3003:
	s_or_b64 exec, exec, s[20:21]
	v_mov_b32_e32 v105, 0
	v_mov_b32_e32 v106, 0
	v_mov_b32_e32 v107, 0
	s_and_saveexec_b64 s[20:21], vcc
	s_cbranch_execz .LBB0_3005
	v_add_u32_e32 v104, 32, v116
	v_ashrrev_i32_e32 v105, 31, v104
	v_mul_lo_u32 v106, s86, v105
	v_mul_lo_u32 v107, s87, v104
	v_mad_u64_u32 v[104:105], s[22:23], s86, v104, 0
	v_add3_u32 v105, v105, v106, v107
	v_lshl_add_u64 v[104:105], v[104:105], 2, v[134:135]
	global_load_dwordx4 v[104:107], v[104:105], off nt
.LBB0_3005:
	s_or_b64 exec, exec, s[20:21]
	v_mov_b32_e32 v111, 0
	v_mov_b32_e32 v112, 0
	v_mov_b32_e32 v113, 0
	v_mov_b32_e32 v114, 0
	v_mov_b32_e32 v115, 0
	s_and_saveexec_b64 s[20:21], vcc
	s_cbranch_execz .LBB0_3007
	v_add_u32_e32 v108, 64, v116
	v_ashrrev_i32_e32 v109, 31, v108
	v_mul_lo_u32 v110, s86, v109
	v_mul_lo_u32 v112, s87, v108
	v_mad_u64_u32 v[108:109], s[22:23], s86, v108, 0
	v_add3_u32 v109, v109, v110, v112
	v_lshl_add_u64 v[108:109], v[108:109], 2, v[134:135]
	global_load_dwordx4 v[112:115], v[108:109], off nt
.LBB0_3007:
	s_or_b64 exec, exec, s[20:21]
	v_mov_b32_e32 v110, 0
	v_mov_b32_e32 v109, 0
	v_mov_b32_e32 v108, 0
	s_and_saveexec_b64 s[20:21], vcc
	s_cbranch_execz .LBB0_3009
	v_add_u32_e32 v108, 0x60, v116
	v_ashrrev_i32_e32 v109, 31, v108
	v_mul_lo_u32 v110, s86, v109
	v_mul_lo_u32 v111, s87, v108
	v_mad_u64_u32 v[108:109], s[22:23], s86, v108, 0
	v_add3_u32 v109, v109, v110, v111
	v_lshl_add_u64 v[108:109], v[108:109], 2, v[134:135]
	global_load_dwordx4 v[108:111], v[108:109], off nt

.LBB0_3010:
	s_cmp_lt_i32 s15, s42
	s_cselect_b64 s[78:79], -1, 0
	s_cmp_ge_i32 s15, s42
	s_cbranch_scc1 .LBB0_3020
	v_add_u32_e32 v136, s8, v133
	v_mov_b32_e32 v120, 0
	v_mov_b32_e32 v116, 0
	v_mov_b32_e32 v117, 0
	v_mov_b32_e32 v118, 0
	v_mov_b32_e32 v119, 0
	s_and_saveexec_b64 s[20:21], vcc
	s_cbranch_execz .LBB0_3013
	v_ashrrev_i32_e32 v116, 31, v136
	v_mul_lo_u32 v118, s87, v136
	v_mul_lo_u32 v119, s86, v116
	v_mad_u64_u32 v[116:117], s[22:23], s86, v136, 0
	v_add3_u32 v117, v117, v119, v118
	v_lshl_add_u64 v[116:117], v[116:117], 2, v[134:135]
	global_load_dwordx4 v[116:119], v[116:117], off nt
.LBB0_3013:
	s_or_b64 exec, exec, s[20:21]
	v_mov_b32_e32 v121, 0
	v_mov_b32_e32 v122, 0
	v_mov_b32_e32 v123, 0
	s_and_saveexec_b64 s[20:21], vcc
	s_cbranch_execz .LBB0_3015
	v_add_u32_e32 v120, 32, v136
	v_ashrrev_i32_e32 v121, 31, v120
	v_mul_lo_u32 v122, s86, v121
	v_mul_lo_u32 v123, s87, v120
	v_mad_u64_u32 v[120:121], s[22:23], s86, v120, 0
	v_add3_u32 v121, v121, v122, v123
	v_lshl_add_u64 v[120:121], v[120:121], 2, v[134:135]
	global_load_dwordx4 v[120:123], v[120:121], off nt
.LBB0_3015:
	s_or_b64 exec, exec, s[20:21]
	v_mov_b32_e32 v127, 0
	v_mov_b32_e32 v128, 0
	v_mov_b32_e32 v129, 0
	v_mov_b32_e32 v130, 0
	v_mov_b32_e32 v131, 0
	s_and_saveexec_b64 s[20:21], vcc
	s_cbranch_execz .LBB0_3017
	v_add_u32_e32 v124, 64, v136
	v_ashrrev_i32_e32 v125, 31, v124
	v_mul_lo_u32 v126, s86, v125
	v_mul_lo_u32 v128, s87, v124
	v_mad_u64_u32 v[124:125], s[22:23], s86, v124, 0
	v_add3_u32 v125, v125, v126, v128
	v_lshl_add_u64 v[124:125], v[124:125], 2, v[134:135]
	global_load_dwordx4 v[128:131], v[124:125], off nt
.LBB0_3017:
	s_or_b64 exec, exec, s[20:21]
	v_mov_b32_e32 v126, 0
	v_mov_b32_e32 v125, 0
	v_mov_b32_e32 v124, 0
	s_and_saveexec_b64 s[20:21], vcc
	s_cbranch_execz .LBB0_3019
	v_add_u32_e32 v124, 0x60, v136
	v_ashrrev_i32_e32 v125, 31, v124
	v_mul_lo_u32 v126, s86, v125
	v_mul_lo_u32 v127, s87, v124
	v_mad_u64_u32 v[124:125], s[22:23], s86, v124, 0
	v_add3_u32 v125, v125, v126, v127
	v_lshl_add_u64 v[124:125], v[124:125], 2, v[134:135]
	global_load_dwordx4 v[124:127], v[124:125], off nt
